# early L2 write-back: the first arriver of each XCD issues buffer_wbl2 sc1 before polling, so the leader's final flush is shorter (on keep_v7)
# speedup vs baseline: 1.0318x; 1.0024x over previous
.LBB0_138:
	s_or_b64 exec, exec, s[14:15]
	v_cvt_f32_u32_e32 v5, v3
	s_waitcnt vmcnt(0)
	v_readfirstlane_b32 s9, v4
	v_sub_u32_e32 v4, 0, v3
	v_rcp_iflag_f32_e32 v5, v5
	v_add_u32_e32 v6, s9, v0
	v_mul_f32_e32 v5, 0x4f7ffffe, v5
	v_cvt_u32_f32_e32 v5, v5
	v_mul_lo_u32 v0, v4, v5
	v_mul_hi_u32 v0, v5, v0
	v_add_u32_e32 v0, v5, v0
	v_mul_hi_u32 v0, v6, v0
	v_mul_lo_u32 v4, v0, v3
	v_sub_u32_e32 v4, v6, v4
	v_add_u32_e32 v5, 1, v0
	v_cmp_ge_u32_e32 vcc, v4, v3
	s_nop 1
	v_cndmask_b32_e32 v0, v0, v5, vcc
	v_sub_u32_e32 v5, v4, v3
	v_cndmask_b32_e32 v4, v4, v5, vcc
	v_add_u32_e32 v5, 1, v0
	v_cmp_ge_u32_e32 vcc, v4, v3
	v_add_u32_e32 v4, 1, v6
	s_nop 0
	v_cndmask_b32_e32 v0, v0, v5, vcc
	v_mul_lo_u32 v5, v3, v0
	v_add_u32_e32 v3, v5, v3
	v_cmp_ne_u32_e32 vcc, v4, v3
	s_and_saveexec_b64 s[12:13], vcc
	s_xor_b64 s[12:13], exec, s[12:13]
	s_cbranch_execz .LBB0_152
	s_waitcnt lgkmcnt(0)
	v_sub_u32_e32 v6, v3, v4
	v_cmp_lt_u32_e32 vcc, 30, v6
	s_cbranch_vccz .Lnowb_0
	buffer_wbl2 sc1
.Lnowb_0:
	s_add_u32 s18, s4, 0x303400
	s_addc_u32 s19, s5, 0
	v_add_u32_e32 v5, 1, v0
	v_mul_lo_u32 v5, v5, v2
	global_load_dword v2, v1, s[18:19] sc1
	s_waitcnt vmcnt(0)
	v_cmp_lt_u32_e32 vcc, v2, v5
	s_and_saveexec_b64 s[14:15], vcc
	s_cbranch_execz .LBB0_151
	s_add_u32 s16, s4, 0x300200
	s_addc_u32 s17, s5, 0
	s_mov_b32 s9, 1
	s_mov_b64 s[22:23], 0
	s_branch .LBB0_142

.Lnowb_7:
	s_add_u32 s24, s4, 0x303400
	s_addc_u32 s25, s5, 0
	v_add_u32_e32 v5, 1, v0
	v_mul_lo_u32 v5, v5, v2
	global_load_dword v2, v1, s[24:25] sc1
	s_waitcnt vmcnt(0)
	v_cmp_lt_u32_e32 vcc, v2, v5
	s_and_saveexec_b64 s[14:15], vcc
	s_cbranch_execz .LBB0_815
	s_add_u32 s22, s4, 0x300200
	s_addc_u32 s23, s5, 0
	s_mov_b32 s9, 1
	s_mov_b64 s[26:27], 0
	s_branch .LBB0_806
